# retention chunk-output item prologue: 16 serialized load-wait-LDS-write round trips replaced by 16 loads in flight with counted waits; plus w_out context prelude 4 iterations in flight
# baseline (speedup 1.0000x reference)
; DEV void retout_item(const Params& p, int l, int bh, int cid, int dry) {
;     ...
;   const u16* Q = (const u16*)(p.ws + OFF_RQ) + ((size_t)bh * UU + u0) * 256;
;   const u16* VTp = (const u16*)(p.ws + OFF_VT) + (size_t)bh * 256 * UU + u0;
;   const float l2gf = -__expf(p.ret_decay[l * 8 + h]) * 1.4426950408889634f;
;   const float l2gb = -__expf(p.ret_decay[l * 8 + 4 + h]) * 1.4426950408889634f;
;   u16* Ql = (u16*)g_shm;
;   u16* Kl = (u16*)(g_shm + 128 * 528);
;   u16* Pl = Kl;
;   float* red = (float*)(g_shm + 128 * 528 + 128 * 272);
;   stage_rows(Q, Ql, tid, 0, l2gf, l2gb);
;   {
;     const u16* KTp = (const u16*)(p.ws + OFF_KT) + (size_t)bh * 256 * UU + (size_t)cid * 32768;
; #pragma unroll
;     for (int i = 0; i < 8; ++i) {
;       const int pc = tid + i * 512;
;       const int lp = pc & 63, ks_ = (pc >> 6) & 7, dk = (pc >> 9) * 32 + (lp & 31), t0 = ks_ * 16 + (lp >> 5) * 8;
;       const bf16x8 v = *reinterpret_cast<const bf16x8*>(KTp + (size_t)pc * 8);
; #pragma unroll
;       for (int e = 0; e < 8; ++e) Kl[(t0 + e) * 264 + dk] = (u16)v[e];
;     }
;   }
.LBB0_32:
	s_mul_hi_i32 s0, s52, 0x78787879
	s_lshr_b32 s1, s0, 31
	s_ashr_i32 s34, s0, 4
	s_add_i32 s34, s34, s1
	s_mul_i32 s0, s34, 34
	s_sub_i32 s0, s52, s0
	s_cmp_gt_i32 s0, 1
	s_cselect_b64 s[4:5], -1, 0
	s_cmp_lt_i32 s0, 2
	s_cselect_b64 s[8:9], -1, 0
	s_and_b64 s[8:9], s[2:3], s[8:9]
	s_and_b64 vcc, exec, s[8:9]
	s_cbranch_vccnz .LBB0_31
	s_lshl_b32 s56, s0, 7
	s_and_b32 s53, s34, 3
	s_mul_i32 s8, s34, 0x1100
	s_ashr_i32 s33, s56, 31
	s_mul_hi_i32 s1, s34, 0x1100
	s_add_u32 s8, s8, s56
	s_addc_u32 s9, s1, s33
	s_lshl_b64 s[8:9], s[8:9], 9
	v_mov_b32_e32 v82, v252
	s_add_u32 s10, s14, s8
	s_addc_u32 s11, s15, s9
	s_or_b32 s12, s53, s43
	v_lshlrev_b32_e32 v0, 3, v82
	s_ashr_i32 s13, s12, 31
	v_readlane_b32 s16, v254, 20
	v_and_b32_e32 v64, 0xf8, v0
	v_ashrrev_i32_e32 v66, 5, v82
	s_lshl_b64 s[12:13], s[12:13], 2
	v_readlane_b32 s30, v254, 34
	v_lshlrev_b32_e32 v162, 1, v64
	v_ashrrev_i32_e32 v67, 31, v66
	v_readlane_b32 s31, v254, 35
	s_add_u32 s12, s30, s12
	v_lshl_add_u64 v[18:19], s[10:11], 0, v[162:163]
	v_lshlrev_b64 v[0:1], 9, v[66:67]
	s_addc_u32 s13, s31, s13
	v_lshl_add_u64 v[4:5], v[18:19], 0, v[0:1]
	global_load_dword v84, v163, s[12:13]
	global_load_dword v89, v163, s[12:13] offset:16
	global_load_dwordx4 v[104:107], v[4:5], off
	v_add_u32_e32 v28, 0x200, v82
	v_add_u32_e32 v21, 0, v162
	v_mul_lo_u32 v6, v66, s37
	v_ashrrev_i32_e32 v68, 5, v28
	v_add_u32_e32 v96, v21, v6
	v_ashrrev_i32_e32 v69, 31, v68
	v_add_u32_e32 v26, 0x400, v82
	v_mul_lo_u32 v8, v68, s37
	v_ashrrev_i32_e32 v70, 5, v26
	v_add_u32_e32 v95, v21, v8
	v_ashrrev_i32_e32 v71, 31, v70
	v_add_u32_e32 v24, 0x600, v82
	v_mul_lo_u32 v10, v70, s37
	v_ashrrev_i32_e32 v72, 5, v24
	v_add_u32_e32 v94, v21, v10
	v_ashrrev_i32_e32 v73, 31, v72
	v_add_u32_e32 v22, 0x800, v82
	v_mul_lo_u32 v12, v72, s37
	v_ashrrev_i32_e32 v74, 5, v22
	v_add_u32_e32 v93, v21, v12
	v_ashrrev_i32_e32 v75, 31, v74
	v_add_u32_e32 v20, 0xa00, v82
	v_mul_lo_u32 v14, v74, s37
	v_ashrrev_i32_e32 v76, 5, v20
	v_add_u32_e32 v92, v21, v14
	v_ashrrev_i32_e32 v77, 31, v76
	v_mul_lo_u32 v16, v76, s37
	v_add_u32_e32 v91, v21, v16
	s_mul_hi_i32 s9, s34, 0x110000
	s_mul_i32 s8, s34, 0x110000
	s_lshl_b64 s[8:9], s[8:9], 1
	s_add_u32 s35, s46, s8
	s_addc_u32 s36, s47, s9
	s_ashr_i32 s1, s0, 31
	s_lshl_b64 s[10:11], s[0:1], 15
	s_lshl_b64 s[12:13], s[0:1], 16
	s_add_u32 s12, s35, s12
	s_addc_u32 s13, s36, s13
	v_ashrrev_i32_e32 v83, 31, v82
	v_and_b32_e32 v97, 31, v82
	v_ashrrev_i32_e32 v29, 31, v28
	v_ashrrev_i32_e32 v27, 31, v26
	v_ashrrev_i32_e32 v25, 31, v24
	v_ashrrev_i32_e32 v23, 31, v22
	v_ashrrev_i32_e32 v86, 6, v82
	v_and_b32_e32 v100, 1, v86
	v_lshlrev_b32_e32 v99, 6, v100
	v_bfe_u32 v98, v82, 5, 1
	v_lshlrev_b32_e32 v87, 4, v98
	v_mov_b32_e32 v247, 0x7f800000
	v_mov_b32_e32 v246, 0x358637bd
	v_and_b32_e32 v88, 63, v82
	v_readlane_b32 s17, v254, 21
	v_readlane_b32 s18, v254, 22
	v_readlane_b32 s19, v254, 23
	v_readlane_b32 s20, v254, 24
	v_readlane_b32 s21, v254, 25
	v_readlane_b32 s22, v254, 26
	v_readlane_b32 s23, v254, 27
	v_readlane_b32 s24, v254, 28
	v_readlane_b32 s25, v254, 29
	v_readlane_b32 s26, v254, 30
	v_readlane_b32 s27, v254, 31
	v_readlane_b32 s28, v254, 32
	v_readlane_b32 s29, v254, 33
	v_lshlrev_b64 v[0:1], 9, v[68:69]
	v_lshl_add_u64 v[6:7], v[18:19], 0, v[0:1]
	global_load_dwordx4 v[108:111], v[6:7], off
	v_lshlrev_b64 v[0:1], 9, v[70:71]
	v_lshl_add_u64 v[8:9], v[18:19], 0, v[0:1]
	global_load_dwordx4 v[112:115], v[8:9], off
	v_lshlrev_b64 v[0:1], 9, v[72:73]
	v_lshl_add_u64 v[10:11], v[18:19], 0, v[0:1]
	global_load_dwordx4 v[116:119], v[10:11], off
	v_lshlrev_b64 v[0:1], 9, v[74:75]
	v_lshl_add_u64 v[12:13], v[18:19], 0, v[0:1]
	global_load_dwordx4 v[120:123], v[12:13], off
	v_lshlrev_b64 v[0:1], 9, v[76:77]
	v_lshl_add_u64 v[14:15], v[18:19], 0, v[0:1]
	global_load_dwordx4 v[124:127], v[14:15], off
	v_add_u32_e32 v2, 0xc00, v82
	v_ashrrev_i32_e32 v78, 5, v2
	v_ashrrev_i32_e32 v79, 31, v78
	v_lshlrev_b64 v[0:1], 9, v[78:79]
	v_lshl_add_u64 v[16:17], v[18:19], 0, v[0:1]
	global_load_dwordx4 v[128:131], v[16:17], off
	v_mul_lo_u32 v0, v78, s37
	v_add_u32_e32 v90, v21, v0
	v_add_u32_e32 v0, 0xe00, v82
	v_ashrrev_i32_e32 v80, 5, v0
	v_ashrrev_i32_e32 v81, 31, v80
	v_mul_lo_u32 v1, v80, s37
	v_add_u32_e32 v65, v21, v1
	v_lshrrev_b32_e32 v1, 2, v82
	v_ashrrev_i32_e32 v3, 4, v82
	v_and_b32_e32 v1, 0x78, v1
	v_lshlrev_b32_e32 v3, 1, v3
	v_and_b32_e32 v3, 0xffffffc0, v3
	v_ashrrev_i32_e32 v21, 31, v20
	v_lshlrev_b64 v[30:31], 9, v[80:81]
	v_lshl_add_u64 v[18:19], v[18:19], 0, v[30:31]
	global_load_dwordx4 v[132:135], v[18:19], off
	v_lshl_add_u64 v[32:33], v[82:83], 4, s[12:13]
	global_load_dwordx4 v[136:139], v[32:33], off
	v_lshl_add_u32 v30, v97, 1, s38
	v_mul_u32_u24_e32 v31, 0x210, v1
	v_add3_u32 v172, v30, v3, v31
	v_ashrrev_i32_e32 v3, 31, v2
	v_ashrrev_i32_e32 v83, 2, v82
	v_ashrrev_i32_e32 v1, 4, v28
	v_lshl_add_u64 v[28:29], v[28:29], 4, s[12:13]
	global_load_dwordx4 v[140:143], v[28:29], off
	v_lshlrev_b32_e32 v1, 1, v1
	v_and_b32_e32 v1, 0xffffffc0, v1
	v_add3_u32 v173, v30, v1, v31
	v_ashrrev_i32_e32 v1, 4, v26
	v_lshl_add_u64 v[26:27], v[26:27], 4, s[12:13]
	global_load_dwordx4 v[144:147], v[26:27], off
	v_lshlrev_b32_e32 v1, 1, v1
	v_and_b32_e32 v1, 0xffffffc0, v1
	v_add3_u32 v174, v30, v1, v31
	v_ashrrev_i32_e32 v1, 4, v24
	v_lshl_add_u64 v[24:25], v[24:25], 4, s[12:13]
	global_load_dwordx4 v[148:151], v[24:25], off
	v_lshlrev_b32_e32 v1, 1, v1
	v_and_b32_e32 v1, 0xffffffc0, v1
	v_add3_u32 v175, v30, v1, v31
	v_ashrrev_i32_e32 v1, 4, v22
	v_lshl_add_u64 v[22:23], v[22:23], 4, s[12:13]
	global_load_dwordx4 v[152:155], v[22:23], off
	v_lshlrev_b32_e32 v1, 1, v1
	v_and_b32_e32 v1, 0xffffffc0, v1
	v_add3_u32 v176, v30, v1, v31
	v_ashrrev_i32_e32 v1, 4, v20
	v_lshl_add_u64 v[20:21], v[20:21], 4, s[12:13]
	global_load_dwordx4 v[156:159], v[20:21], off
	v_lshlrev_b32_e32 v1, 1, v1
	v_and_b32_e32 v1, 0xffffffc0, v1
	v_add3_u32 v177, v30, v1, v31
	v_ashrrev_i32_e32 v1, 4, v2
	v_lshl_add_u64 v[2:3], v[2:3], 4, s[12:13]
	global_load_dwordx4 v[164:167], v[2:3], off
	v_lshlrev_b32_e32 v1, 1, v1
	v_and_b32_e32 v1, 0xffffffc0, v1
	v_add3_u32 v178, v30, v1, v31
	v_ashrrev_i32_e32 v2, 4, v0
	v_lshlrev_b32_e32 v2, 1, v2
	v_and_b32_e32 v2, 0xffffffc0, v2
	v_ashrrev_i32_e32 v1, 31, v0
	v_lshl_add_u64 v[0:1], v[0:1], 4, s[12:13]
	v_add3_u32 v179, v30, v2, v31
	global_load_dwordx4 v[168:171], v[0:1], off
	s_movk_i32 s12, 0x4200
	s_waitcnt vmcnt(15)
; DEV void retout_item(const Params& p, int l, int bh, int cid, int dry) {
;     ...
;   stage_rows(Q, Ql, tid, 0, l2gf, l2gb);
;   {
;     const u16* KTp = (const u16*)(p.ws + OFF_KT) + (size_t)bh * 256 * UU + (size_t)cid * 32768;
; #pragma unroll
;     for (int i = 0; i < 8; ++i) {
;       const int pc = tid + i * 512;
;       const int lp = pc & 63, ks_ = (pc >> 6) & 7, dk = (pc >> 9) * 32 + (lp & 31), t0 = ks_ * 16 + (lp >> 5) * 8;
;       const bf16x8 v = *reinterpret_cast<const bf16x8*>(KTp + (size_t)pc * 8);
; #pragma unroll
;       for (int e = 0; e < 8; ++e) Kl[(t0 + e) * 264 + dk] = (u16)v[e];
;     }
;   }
;   __syncthreads();
;   bf16x8 qreg[8];
;   load_rows(Q, qreg, tid);
;   {
;     const int wr4 = wid >> 1, wc2 = wid & 1;
;     f32x16 s0 = {}, s1 = {};
	ds_write_b128 v96, v[104:107]
	s_waitcnt vmcnt(14)
	ds_write_b128 v95, v[108:111]
	s_waitcnt vmcnt(13)
	ds_write_b128 v94, v[112:115]
	s_waitcnt vmcnt(12)
	ds_write_b128 v93, v[116:119]
	s_waitcnt vmcnt(11)
	ds_write_b128 v92, v[120:123]
	s_waitcnt vmcnt(10)
	ds_write_b128 v91, v[124:127]
	s_waitcnt vmcnt(9)
	ds_write_b128 v90, v[128:131]
	s_waitcnt vmcnt(8)
	ds_write_b128 v65, v[132:135]
	s_waitcnt vmcnt(7)
	ds_write_b16 v172, v136
	ds_write_b16_d16_hi v172, v136 offset:528
	ds_write_b16 v172, v137 offset:1056
	ds_write_b16_d16_hi v172, v137 offset:1584
	ds_write_b16 v172, v138 offset:2112
	ds_write_b16_d16_hi v172, v138 offset:2640
	ds_write_b16 v172, v139 offset:3168
	ds_write_b16_d16_hi v172, v139 offset:3696
	s_waitcnt vmcnt(6)
	ds_write_b16 v173, v140
	ds_write_b16_d16_hi v173, v140 offset:528
	ds_write_b16 v173, v141 offset:1056
	ds_write_b16_d16_hi v173, v141 offset:1584
	ds_write_b16 v173, v142 offset:2112
	ds_write_b16_d16_hi v173, v142 offset:2640
	ds_write_b16 v173, v143 offset:3168
	ds_write_b16_d16_hi v173, v143 offset:3696
	s_waitcnt vmcnt(5)
	ds_write_b16 v174, v144
	ds_write_b16_d16_hi v174, v144 offset:528
	ds_write_b16 v174, v145 offset:1056
	ds_write_b16_d16_hi v174, v145 offset:1584
	ds_write_b16 v174, v146 offset:2112
	ds_write_b16_d16_hi v174, v146 offset:2640
	ds_write_b16 v174, v147 offset:3168
	ds_write_b16_d16_hi v174, v147 offset:3696
	s_waitcnt vmcnt(4)
	ds_write_b16 v175, v148
	ds_write_b16_d16_hi v175, v148 offset:528
	ds_write_b16 v175, v149 offset:1056
	ds_write_b16_d16_hi v175, v149 offset:1584
	ds_write_b16 v175, v150 offset:2112
	ds_write_b16_d16_hi v175, v150 offset:2640
	ds_write_b16 v175, v151 offset:3168
	ds_write_b16_d16_hi v175, v151 offset:3696
	s_waitcnt vmcnt(3)
	ds_write_b16 v176, v152
	ds_write_b16_d16_hi v176, v152 offset:528
	ds_write_b16 v176, v153 offset:1056
	ds_write_b16_d16_hi v176, v153 offset:1584
	ds_write_b16 v176, v154 offset:2112
	ds_write_b16_d16_hi v176, v154 offset:2640
	ds_write_b16 v176, v155 offset:3168
	ds_write_b16_d16_hi v176, v155 offset:3696
	s_waitcnt vmcnt(2)
	ds_write_b16 v177, v156
	ds_write_b16_d16_hi v177, v156 offset:528
	ds_write_b16 v177, v157 offset:1056
	ds_write_b16_d16_hi v177, v157 offset:1584
	ds_write_b16 v177, v158 offset:2112
	ds_write_b16_d16_hi v177, v158 offset:2640
	ds_write_b16 v177, v159 offset:3168
	ds_write_b16_d16_hi v177, v159 offset:3696
	s_waitcnt vmcnt(1)
	ds_write_b16 v178, v164
	ds_write_b16_d16_hi v178, v164 offset:528
	ds_write_b16 v178, v165 offset:1056
	ds_write_b16_d16_hi v178, v165 offset:1584
	ds_write_b16 v178, v166 offset:2112
	ds_write_b16_d16_hi v178, v166 offset:2640
	ds_write_b16 v178, v167 offset:3168
	ds_write_b16_d16_hi v178, v167 offset:3696
	s_waitcnt vmcnt(0)
	ds_write_b16 v179, v168
	ds_write_b16_d16_hi v179, v168 offset:528
	ds_write_b16 v179, v169 offset:1056
	ds_write_b16_d16_hi v179, v169 offset:1584
	ds_write_b16 v179, v170 offset:2112
	ds_write_b16_d16_hi v179, v170 offset:2640
	ds_write_b16 v179, v171 offset:3168
	ds_write_b16_d16_hi v179, v171 offset:3696
	s_waitcnt lgkmcnt(0)
	s_barrier
	global_load_dwordx4 v[60:63], v[4:5], off
	global_load_dwordx4 v[56:59], v[6:7], off
	global_load_dwordx4 v[52:55], v[8:9], off
	global_load_dwordx4 v[48:51], v[10:11], off
	global_load_dwordx4 v[44:47], v[12:13], off
	global_load_dwordx4 v[40:43], v[14:15], off
	global_load_dwordx4 v[36:39], v[16:17], off
	global_load_dwordx4 v[32:35], v[18:19], off
	v_or_b32_e32 v0, v99, v97
	v_mul_u32_u24_e32 v0, 0x210, v0
	v_add3_u32 v85, v0, v87, 0
	v_lshrrev_b32_e32 v0, 5, v83
	v_mul_lo_u32 v0, v0, s12
	v_mad_u32_u24 v0, v97, s37, v0
	v_mov_b32_e32 v16, 0
	v_add3_u32 v101, v0, v87, 0
	s_mov_b32 s12, 0
	v_mov_b32_e32 v17, v16
	v_mov_b32_e32 v18, v16
	v_mov_b32_e32 v19, v16
	v_mov_b32_e32 v20, v16
	v_mov_b32_e32 v21, v16
	v_mov_b32_e32 v22, v16
	v_mov_b32_e32 v23, v16
	v_mov_b32_e32 v24, v16
	v_mov_b32_e32 v25, v16
	v_mov_b32_e32 v26, v16
	v_mov_b32_e32 v27, v16
	v_mov_b32_e32 v28, v16
	v_mov_b32_e32 v29, v16
	v_mov_b32_e32 v30, v16
	v_mov_b32_e32 v31, v16
	v_mov_b32_e32 v0, v16
	v_mov_b32_e32 v1, v16
	v_mov_b32_e32 v2, v16
	v_mov_b32_e32 v3, v16
	v_mov_b32_e32 v4, v16
	v_mov_b32_e32 v5, v16
	v_mov_b32_e32 v6, v16
	v_mov_b32_e32 v7, v16
	v_mov_b32_e32 v8, v16
	v_mov_b32_e32 v9, v16
	v_mov_b32_e32 v10, v16
	v_mov_b32_e32 v11, v16
	v_mov_b32_e32 v12, v16
	v_mov_b32_e32 v13, v16
	v_mov_b32_e32 v14, v16
	v_mov_b32_e32 v15, v16

; DEV void phase_gemm(const Params& p, int l, int mode) {
;     ...
;   if (mode == 2 && extra_pending) {
;     const float* P0 = (const float*)(p.ws + OFF_MFC) + (size_t)((cu >> 2) * 256) * 1024;
;     u16* dst = (u16*)(p.ws + OFF_SCA) + (size_t)cu * 256 * 1024;
; #pragma unroll 2
;     for (int idx = tid; idx < 256 * 128; idx += 512) {
;       const size_t o = (size_t)idx * 8;
;       f32x4 a0 = *reinterpret_cast<const f32x4*>(P0 + o), a1 = *reinterpret_cast<const f32x4*>(P0 + o + 4);
;       a0 += *reinterpret_cast<const f32x4*>(P0 + 1048576 + o); a1 += *reinterpret_cast<const f32x4*>(P0 + 1048576 + o + 4);
;       a0 += *reinterpret_cast<const f32x4*>(P0 + 2097152 + o); a1 += *reinterpret_cast<const f32x4*>(P0 + 2097152 + o + 4);
;       *reinterpret_cast<u32x4*>(dst + o) = pack8(a0, a1, 1.f);
;     }
;     asm volatile("s_waitcnt vmcnt(0)" ::: "memory");
;     __syncthreads();
;   }
.LBB0_182:
	s_mov_b32 s5, 0
.Lpre_sum4:
	v_lshl_add_u64 v[24:25], v[2:3], 0, s[82:83]
	v_add_co_u32_e32 v8, vcc, 0x3a649000, v24
	s_mov_b64 s[14:15], 0x3a649700
	s_nop 0
	v_addc_co_u32_e32 v9, vcc, 0, v25, vcc
	v_lshl_add_u64 v[12:13], v[24:25], 0, s[14:15]
	s_mov_b64 s[14:15], 0x3aa49700
	v_add_co_u32_e32 v16, vcc, 0x3aa49000, v24
	v_lshl_add_u64 v[20:21], v[24:25], 0, s[14:15]
	s_mov_b64 s[14:15], 0x3ae49700
	s_nop 0
	v_addc_co_u32_e32 v17, vcc, 0, v25, vcc
	v_lshl_add_u64 v[28:29], v[24:25], 0, s[14:15]
	v_add_co_u32_e32 v24, vcc, 0x3ae49000, v24
	global_load_dwordx4 v[8:11], v[8:9], off offset:1792
	s_nop 0
	global_load_dwordx4 v[12:15], v[12:13], off offset:16
	s_nop 0
	global_load_dwordx4 v[16:19], v[16:17], off offset:1792
	s_nop 0
	global_load_dwordx4 v[20:23], v[20:21], off offset:16
	v_addc_co_u32_e32 v25, vcc, 0, v25, vcc
	global_load_dwordx4 v[24:27], v[24:25], off offset:1792
	s_nop 0
	global_load_dwordx4 v[28:31], v[28:29], off offset:16
	v_lshl_add_u64 v[32:33], v[4:5], 0, s[82:83]
	v_lshl_add_u64 v[2:3], v[2:3], 0, s[16:17]
	v_lshl_add_u64 v[4:5], v[4:5], 0, s[18:19]
	v_lshl_add_u64 v[50:51], v[2:3], 0, s[82:83]
	v_add_co_u32_e32 v34, vcc, 0x3a649000, v50
	s_mov_b64 s[14:15], 0x3a649700
	s_nop 0
	v_addc_co_u32_e32 v35, vcc, 0, v51, vcc
	v_lshl_add_u64 v[38:39], v[50:51], 0, s[14:15]
	s_mov_b64 s[14:15], 0x3aa49700
	v_add_co_u32_e32 v42, vcc, 0x3aa49000, v50
	v_lshl_add_u64 v[46:47], v[50:51], 0, s[14:15]
	s_mov_b64 s[14:15], 0x3ae49700
	s_nop 0
	v_addc_co_u32_e32 v43, vcc, 0, v51, vcc
	v_lshl_add_u64 v[54:55], v[50:51], 0, s[14:15]
	v_add_co_u32_e32 v50, vcc, 0x3ae49000, v50
	global_load_dwordx4 v[34:37], v[34:35], off offset:1792
	s_nop 0
	global_load_dwordx4 v[38:41], v[38:39], off offset:16
	s_nop 0
	global_load_dwordx4 v[42:45], v[42:43], off offset:1792
	s_nop 0
	global_load_dwordx4 v[46:49], v[46:47], off offset:16
	v_addc_co_u32_e32 v51, vcc, 0, v51, vcc
	global_load_dwordx4 v[50:53], v[50:51], off offset:1792
	s_nop 0
	global_load_dwordx4 v[54:57], v[54:55], off offset:16
	v_lshl_add_u64 v[58:59], v[4:5], 0, s[82:83]
	v_lshl_add_u64 v[2:3], v[2:3], 0, s[16:17]
	v_lshl_add_u64 v[4:5], v[4:5], 0, s[18:19]
	v_lshl_add_u64 v[76:77], v[2:3], 0, s[82:83]
	v_add_co_u32_e32 v60, vcc, 0x3a649000, v76
	s_mov_b64 s[14:15], 0x3a649700
	s_nop 0
	v_addc_co_u32_e32 v61, vcc, 0, v77, vcc
	v_lshl_add_u64 v[64:65], v[76:77], 0, s[14:15]
	s_mov_b64 s[14:15], 0x3aa49700
	v_add_co_u32_e32 v68, vcc, 0x3aa49000, v76
	v_lshl_add_u64 v[72:73], v[76:77], 0, s[14:15]
	s_mov_b64 s[14:15], 0x3ae49700
	s_nop 0
	v_addc_co_u32_e32 v69, vcc, 0, v77, vcc
	v_lshl_add_u64 v[80:81], v[76:77], 0, s[14:15]
	v_add_co_u32_e32 v76, vcc, 0x3ae49000, v76
	global_load_dwordx4 v[60:63], v[60:61], off offset:1792
	s_nop 0
	global_load_dwordx4 v[64:67], v[64:65], off offset:16
	s_nop 0
	global_load_dwordx4 v[68:71], v[68:69], off offset:1792
	s_nop 0
	global_load_dwordx4 v[72:75], v[72:73], off offset:16
	v_addc_co_u32_e32 v77, vcc, 0, v77, vcc
	global_load_dwordx4 v[76:79], v[76:77], off offset:1792
	s_nop 0
	global_load_dwordx4 v[80:83], v[80:81], off offset:16
	v_lshl_add_u64 v[84:85], v[4:5], 0, s[82:83]
	v_lshl_add_u64 v[2:3], v[2:3], 0, s[16:17]
	v_lshl_add_u64 v[4:5], v[4:5], 0, s[18:19]
	v_lshl_add_u64 v[102:103], v[2:3], 0, s[82:83]
	v_add_co_u32_e32 v86, vcc, 0x3a649000, v102
	s_mov_b64 s[14:15], 0x3a649700
	s_nop 0
	v_addc_co_u32_e32 v87, vcc, 0, v103, vcc
	v_lshl_add_u64 v[90:91], v[102:103], 0, s[14:15]
	s_mov_b64 s[14:15], 0x3aa49700
	v_add_co_u32_e32 v94, vcc, 0x3aa49000, v102
	v_lshl_add_u64 v[98:99], v[102:103], 0, s[14:15]
	s_mov_b64 s[14:15], 0x3ae49700
	s_nop 0
	v_addc_co_u32_e32 v95, vcc, 0, v103, vcc
	v_lshl_add_u64 v[106:107], v[102:103], 0, s[14:15]
	v_add_co_u32_e32 v102, vcc, 0x3ae49000, v102
	global_load_dwordx4 v[86:89], v[86:87], off offset:1792
	s_nop 0
	global_load_dwordx4 v[90:93], v[90:91], off offset:16
	s_nop 0
	global_load_dwordx4 v[94:97], v[94:95], off offset:1792
	s_nop 0
	global_load_dwordx4 v[98:101], v[98:99], off offset:16
	v_addc_co_u32_e32 v103, vcc, 0, v103, vcc
	global_load_dwordx4 v[102:105], v[102:103], off offset:1792
	s_nop 0
	global_load_dwordx4 v[106:109], v[106:107], off offset:16
	v_lshl_add_u64 v[110:111], v[4:5], 0, s[82:83]
	v_lshl_add_u64 v[2:3], v[2:3], 0, s[16:17]
	v_lshl_add_u64 v[4:5], v[4:5], 0, s[18:19]
	s_waitcnt vmcnt(18)
	v_pk_add_f32 v[10:11], v[10:11], v[18:19]
	v_pk_add_f32 v[8:9], v[8:9], v[16:17]
	v_pk_add_f32 v[14:15], v[14:15], v[22:23]
	v_pk_add_f32 v[12:13], v[12:13], v[20:21]
	v_pk_add_f32 v[10:11], v[10:11], v[26:27]
	v_pk_add_f32 v[8:9], v[8:9], v[24:25]
	v_pk_add_f32 v[14:15], v[14:15], v[30:31]
	v_pk_add_f32 v[12:13], v[12:13], v[28:29]
	v_cvt_pk_bf16_f32 v8, v8, v9
	v_cvt_pk_bf16_f32 v9, v10, v11
	v_cvt_pk_bf16_f32 v11, v14, v15
	s_nop 0
	v_cvt_pk_bf16_f32 v10, v12, v13
	global_store_dwordx4 v[32:33], v[8:11], off
	s_waitcnt vmcnt(13)
	v_pk_add_f32 v[36:37], v[36:37], v[44:45]
	v_pk_add_f32 v[34:35], v[34:35], v[42:43]
	v_pk_add_f32 v[40:41], v[40:41], v[48:49]
	v_pk_add_f32 v[38:39], v[38:39], v[46:47]
	v_pk_add_f32 v[36:37], v[36:37], v[52:53]
	v_pk_add_f32 v[34:35], v[34:35], v[50:51]
	v_pk_add_f32 v[40:41], v[40:41], v[56:57]
	v_pk_add_f32 v[38:39], v[38:39], v[54:55]
	v_cvt_pk_bf16_f32 v34, v34, v35
	v_cvt_pk_bf16_f32 v35, v36, v37
	v_cvt_pk_bf16_f32 v37, v40, v41
	s_nop 0
	v_cvt_pk_bf16_f32 v36, v38, v39
	global_store_dwordx4 v[58:59], v[34:37], off
	s_waitcnt vmcnt(8)
	v_pk_add_f32 v[62:63], v[62:63], v[70:71]
	v_pk_add_f32 v[60:61], v[60:61], v[68:69]
	v_pk_add_f32 v[66:67], v[66:67], v[74:75]
	v_pk_add_f32 v[64:65], v[64:65], v[72:73]
	v_pk_add_f32 v[62:63], v[62:63], v[78:79]
	v_pk_add_f32 v[60:61], v[60:61], v[76:77]
	v_pk_add_f32 v[66:67], v[66:67], v[82:83]
	v_pk_add_f32 v[64:65], v[64:65], v[80:81]
	v_cvt_pk_bf16_f32 v60, v60, v61
	v_cvt_pk_bf16_f32 v61, v62, v63
	v_cvt_pk_bf16_f32 v63, v66, v67
	s_nop 0
	v_cvt_pk_bf16_f32 v62, v64, v65
	global_store_dwordx4 v[84:85], v[60:63], off
	s_waitcnt vmcnt(3)
	v_pk_add_f32 v[88:89], v[88:89], v[96:97]
	v_pk_add_f32 v[86:87], v[86:87], v[94:95]
	v_pk_add_f32 v[92:93], v[92:93], v[100:101]
	v_pk_add_f32 v[90:91], v[90:91], v[98:99]
	v_pk_add_f32 v[88:89], v[88:89], v[104:105]
	v_pk_add_f32 v[86:87], v[86:87], v[102:103]
	v_pk_add_f32 v[92:93], v[92:93], v[108:109]
	v_pk_add_f32 v[90:91], v[90:91], v[106:107]
	v_cvt_pk_bf16_f32 v86, v86, v87
	v_cvt_pk_bf16_f32 v87, v88, v89
	v_cvt_pk_bf16_f32 v89, v92, v93
	s_nop 0
	v_cvt_pk_bf16_f32 v88, v90, v91
	global_store_dwordx4 v[110:111], v[86:89], off
	s_add_i32 s5, s5, 1
	s_cmp_lt_u32 s5, 16
	s_cbranch_scc1 .Lpre_sum4
